# code placement: the four K-loop bodies (P1/P4 loop and peeled first iteration) start on 64-byte boundaries (.p2align 6 before their labels)
# baseline (speedup 1.0000x reference)
; template <class Epi, class Sched, bool ALIGN_EPI = false, bool SP2 = false>
; __device__ __forceinline__ void gemm_phase(PG8_LAS unsigned char* lds, const Gemm g, const Sched& S, const Epi& E) {
;     ...
;         const bool has_next = S.next(ui + 1, nxt);
;         const char* nA = has_next ? (const char*)g.A + (size_t)nxt.pm * tstep : cA; const char* nB = has_next ? (const char*)g.Bt + (size_t)nxt.pn * tstep : cB;
;         for (int t = 0; t < nt; t += 2) {
;             const bool last = (t == nt - 2);
;             const char* a1 = cA + (size_t)(t + 1) * kstep;
;             const char* a2 = last ? nA : cA + (size_t)(t + 2) * kstep; const char* b2 = last ? nB : cB + (size_t)(t + 2) * kstep;
;     ...
; #pragma unroll
;         for (int a = 0; a < 2; ++a)
; #pragma unroll
;             for (int b = 0; b < 2; ++b)
; #pragma unroll
;                 for (int m = 0; m < 4; ++m)
; #pragma unroll
;                     for (int n = 0; n < 2; ++n) acc[a][b][m][n] = (f32x4){0.f, 0.f, 0.f, 0.f};
.LBB0_161:
	s_ashr_i32 s41, s40, 31
	s_lshl_b64 s[34:35], s[40:41], 19
	s_add_u32 s42, s68, s34
	s_addc_u32 s43, s69, s35
	s_and_b64 s[34:35], s[0:1], exec
	s_cselect_b32 s5, s43, s49
	s_cselect_b32 s34, s42, s48
	s_ashr_i32 s27, s26, 31
	s_lshl_b64 s[44:45], s[26:27], 19
	s_add_u32 s44, s70, s44
	s_addc_u32 s45, s71, s45
	s_and_b64 s[64:65], s[0:1], exec
	s_cselect_b32 s27, s45, s51
	s_cselect_b32 s35, s44, s50
	s_add_u32 s48, s48, 0x40080
	s_addc_u32 s49, s49, 0
	s_add_u32 s41, s50, 0x100
	v_mov_b32_e32 v2, 0
	s_addc_u32 s92, s51, 0
	s_mov_b32 s93, -2
	v_mov_b32_e32 v3, v2
	s_cmp_lg_u32 s76, 1
	s_cbranch_scc1 .Lp1_peel
	v_mov_b32_e32 v4, v2
	v_mov_b32_e32 v5, v2
	v_mov_b32_e32 v6, v2
	v_mov_b32_e32 v7, v2
	v_mov_b32_e32 v8, v2
	v_mov_b32_e32 v9, v2
	v_mov_b32_e32 v18, v2
	v_mov_b32_e32 v19, v2
	v_mov_b32_e32 v20, v2
	v_mov_b32_e32 v21, v2
	v_mov_b32_e32 v22, v2
	v_mov_b32_e32 v23, v2
	v_mov_b32_e32 v24, v2
	v_mov_b32_e32 v25, v2
	v_mov_b32_e32 v34, v2
	v_mov_b32_e32 v35, v2
	v_mov_b32_e32 v36, v2
	v_mov_b32_e32 v37, v2
	v_mov_b32_e32 v38, v2
	v_mov_b32_e32 v39, v2
	v_mov_b32_e32 v40, v2
	v_mov_b32_e32 v41, v2
	v_mov_b32_e32 v50, v2
	v_mov_b32_e32 v51, v2
	v_mov_b32_e32 v52, v2
	v_mov_b32_e32 v53, v2
	v_mov_b32_e32 v54, v2
	v_mov_b32_e32 v55, v2
	v_mov_b32_e32 v56, v2
	v_mov_b32_e32 v57, v2
	v_mov_b32_e32 v10, v2
	v_mov_b32_e32 v11, v2
	v_mov_b32_e32 v12, v2
	v_mov_b32_e32 v13, v2
	v_mov_b32_e32 v14, v2
	v_mov_b32_e32 v15, v2
	v_mov_b32_e32 v16, v2
	v_mov_b32_e32 v17, v2
	v_mov_b32_e32 v26, v2
	v_mov_b32_e32 v27, v2
	v_mov_b32_e32 v28, v2
	v_mov_b32_e32 v29, v2
	v_mov_b32_e32 v30, v2
	v_mov_b32_e32 v31, v2
	v_mov_b32_e32 v32, v2
	v_mov_b32_e32 v33, v2
	v_mov_b32_e32 v42, v2
	v_mov_b32_e32 v43, v2
	v_mov_b32_e32 v44, v2
	v_mov_b32_e32 v45, v2
	v_mov_b32_e32 v46, v2
	v_mov_b32_e32 v47, v2
	v_mov_b32_e32 v48, v2
	v_mov_b32_e32 v49, v2
	v_mov_b32_e32 v58, v2
	v_mov_b32_e32 v59, v2
	v_mov_b32_e32 v60, v2
	v_mov_b32_e32 v61, v2
	v_mov_b32_e32 v62, v2
	v_mov_b32_e32 v63, v2
	v_mov_b32_e32 v64, v2
	v_mov_b32_e32 v65, v2
	v_mov_b32_e32 v66, v2
	v_mov_b32_e32 v67, v2
	v_mov_b32_e32 v68, v2
	v_mov_b32_e32 v69, v2
	v_mov_b32_e32 v70, v2
	v_mov_b32_e32 v71, v2
	v_mov_b32_e32 v72, v2
	v_mov_b32_e32 v73, v2
	v_mov_b32_e32 v82, v2
	v_mov_b32_e32 v83, v2
	v_mov_b32_e32 v84, v2
	v_mov_b32_e32 v85, v2
	v_mov_b32_e32 v86, v2
	v_mov_b32_e32 v87, v2
	v_mov_b32_e32 v88, v2
	v_mov_b32_e32 v89, v2
	v_mov_b32_e32 v98, v2
	v_mov_b32_e32 v99, v2
	v_mov_b32_e32 v100, v2
	v_mov_b32_e32 v101, v2
	v_mov_b32_e32 v102, v2
	v_mov_b32_e32 v103, v2
	v_mov_b32_e32 v104, v2
	v_mov_b32_e32 v105, v2
	v_mov_b32_e32 v114, v2
	v_mov_b32_e32 v115, v2
	v_mov_b32_e32 v116, v2
	v_mov_b32_e32 v117, v2
	v_mov_b32_e32 v118, v2
	v_mov_b32_e32 v119, v2
	v_mov_b32_e32 v120, v2
	v_mov_b32_e32 v121, v2
	v_mov_b32_e32 v74, v2
	v_mov_b32_e32 v75, v2
	v_mov_b32_e32 v76, v2
	v_mov_b32_e32 v77, v2
	v_mov_b32_e32 v78, v2
	v_mov_b32_e32 v79, v2
	v_mov_b32_e32 v80, v2
	v_mov_b32_e32 v81, v2
	v_mov_b32_e32 v90, v2
	v_mov_b32_e32 v91, v2
	v_mov_b32_e32 v92, v2
	v_mov_b32_e32 v93, v2
	v_mov_b32_e32 v94, v2
	v_mov_b32_e32 v95, v2
	v_mov_b32_e32 v96, v2
	v_mov_b32_e32 v97, v2
	v_mov_b32_e32 v106, v2
	v_mov_b32_e32 v107, v2
	v_mov_b32_e32 v108, v2
	v_mov_b32_e32 v109, v2
	v_mov_b32_e32 v110, v2
	v_mov_b32_e32 v111, v2
	v_mov_b32_e32 v112, v2
	v_mov_b32_e32 v113, v2
	v_mov_b32_e32 v122, v2
	v_mov_b32_e32 v123, v2
	v_mov_b32_e32 v124, v2
	v_mov_b32_e32 v125, v2
	v_mov_b32_e32 v126, v2
	v_mov_b32_e32 v127, v2
	v_mov_b32_e32 v128, v2
	v_mov_b32_e32 v129, v2
	.p2align	6

; #define PG8_BAR __builtin_amdgcn_s_barrier()
; template <class Epi, class Sched, bool ALIGN_EPI = false, bool SP2 = false>
; __device__ __forceinline__ void gemm_phase(PG8_LAS unsigned char* lds, const Gemm g, const Sched& S, const Epi& E) {
;     ...
;         cur = nxt; cA = nA; cB = nB; ++ui;
;         if constexpr (ALIGN_EPI) { if (wr == 1) PG8_BAR; }
.LBB0_206:
	s_andn2_b64 vcc, exec, s[10:11]
	s_cbranch_vccnz .LBB0_157
	s_barrier
	s_branch .LBB0_157
	.p2align	6

; template <class Epi, class Sched, bool ALIGN_EPI = false, bool SP2 = false>
; __device__ __forceinline__ void gemm_phase(PG8_LAS unsigned char* lds, const Gemm g, const Sched& S, const Epi& E) {
;     ...
;         const bool has_next = S.next(ui + 1, nxt);
;         const char* nA = has_next ? (const char*)g.A + (size_t)nxt.pm * tstep : cA; const char* nB = has_next ? (const char*)g.Bt + (size_t)nxt.pn * tstep : cB;
;         for (int t = 0; t < nt; t += 2) {
;             const bool last = (t == nt - 2);
;             const char* a1 = cA + (size_t)(t + 1) * kstep;
;             const char* a2 = last ? nA : cA + (size_t)(t + 2) * kstep; const char* b2 = last ? nB : cB + (size_t)(t + 2) * kstep;
;     ...
; #pragma unroll
;         for (int a = 0; a < 2; ++a)
; #pragma unroll
;             for (int b = 0; b < 2; ++b)
; #pragma unroll
;                 for (int m = 0; m < 4; ++m)
; #pragma unroll
;                     for (int n = 0; n < 2; ++n) acc[a][b][m][n] = (f32x4){0.f, 0.f, 0.f, 0.f};
.LBB0_456:
	s_ashr_i32 s25, s24, 31
	s_lshl_b64 s[26:27], s[24:25], 19
	s_add_u32 s26, s33, s26
	s_addc_u32 s27, s42, s27
	s_and_b64 s[28:29], s[0:1], exec
	s_cselect_b32 s25, s27, s35
	s_cselect_b32 s61, s26, s34
	s_ashr_i32 s21, s20, 31
	s_lshl_b64 s[28:29], s[20:21], 19
	s_add_u32 s28, s43, s28
	s_addc_u32 s29, s44, s29
	s_and_b64 s[38:39], s[0:1], exec
	s_cselect_b32 s21, s29, s41
	s_cselect_b32 s62, s28, s40
	s_add_u32 s34, s34, 0x40080
	s_addc_u32 s35, s35, 0
	s_add_u32 s63, s40, 0x100
	v_mov_b32_e32 v0, 0
	s_addc_u32 s64, s41, 0
	s_mov_b32 s65, -2
	v_mov_b32_e32 v1, v0
	s_cmp_lg_u32 s51, 1
	s_cbranch_scc1 .Lp4_peel
	v_mov_b32_e32 v2, v0
	v_mov_b32_e32 v3, v0
	v_mov_b32_e32 v4, v0
	v_mov_b32_e32 v5, v0
	v_mov_b32_e32 v6, v0
	v_mov_b32_e32 v7, v0
	v_mov_b32_e32 v8, v0
	v_mov_b32_e32 v9, v0
	v_mov_b32_e32 v10, v0
	v_mov_b32_e32 v11, v0
	v_mov_b32_e32 v16, v0
	v_mov_b32_e32 v17, v0
	v_mov_b32_e32 v18, v0
	v_mov_b32_e32 v19, v0
	v_mov_b32_e32 v28, v0
	v_mov_b32_e32 v29, v0
	v_mov_b32_e32 v30, v0
	v_mov_b32_e32 v31, v0
	v_mov_b32_e32 v32, v0
	v_mov_b32_e32 v33, v0
	v_mov_b32_e32 v34, v0
	v_mov_b32_e32 v35, v0
	v_mov_b32_e32 v40, v0
	v_mov_b32_e32 v41, v0
	v_mov_b32_e32 v42, v0
	v_mov_b32_e32 v43, v0
	v_mov_b32_e32 v44, v0
	v_mov_b32_e32 v45, v0
	v_mov_b32_e32 v46, v0
	v_mov_b32_e32 v47, v0
	v_mov_b32_e32 v12, v0
	v_mov_b32_e32 v13, v0
	v_mov_b32_e32 v14, v0
	v_mov_b32_e32 v15, v0
	v_mov_b32_e32 v20, v0
	v_mov_b32_e32 v21, v0
	v_mov_b32_e32 v22, v0
	v_mov_b32_e32 v23, v0
	v_mov_b32_e32 v24, v0
	v_mov_b32_e32 v25, v0
	v_mov_b32_e32 v26, v0
	v_mov_b32_e32 v27, v0
	v_mov_b32_e32 v36, v0
	v_mov_b32_e32 v37, v0
	v_mov_b32_e32 v38, v0
	v_mov_b32_e32 v39, v0
	v_mov_b32_e32 v48, v0
	v_mov_b32_e32 v49, v0
	v_mov_b32_e32 v50, v0
	v_mov_b32_e32 v51, v0
	v_mov_b32_e32 v52, v0
	v_mov_b32_e32 v53, v0
	v_mov_b32_e32 v54, v0
	v_mov_b32_e32 v55, v0
	v_mov_b32_e32 v56, v0
	v_mov_b32_e32 v57, v0
	v_mov_b32_e32 v58, v0
	v_mov_b32_e32 v59, v0
	v_mov_b32_e32 v60, v0
	v_mov_b32_e32 v61, v0
	v_mov_b32_e32 v62, v0
	v_mov_b32_e32 v63, v0
	v_mov_b32_e32 v64, v0
	v_mov_b32_e32 v65, v0
	v_mov_b32_e32 v66, v0
	v_mov_b32_e32 v67, v0
	v_mov_b32_e32 v68, v0
	v_mov_b32_e32 v69, v0
	v_mov_b32_e32 v70, v0
	v_mov_b32_e32 v71, v0
	v_mov_b32_e32 v72, v0
	v_mov_b32_e32 v73, v0
	v_mov_b32_e32 v74, v0
	v_mov_b32_e32 v75, v0
	v_mov_b32_e32 v80, v0
	v_mov_b32_e32 v81, v0
	v_mov_b32_e32 v82, v0
	v_mov_b32_e32 v83, v0
	v_mov_b32_e32 v92, v0
	v_mov_b32_e32 v93, v0
	v_mov_b32_e32 v94, v0
	v_mov_b32_e32 v95, v0
	v_mov_b32_e32 v100, v0
	v_mov_b32_e32 v101, v0
	v_mov_b32_e32 v102, v0
	v_mov_b32_e32 v103, v0
	v_mov_b32_e32 v104, v0
	v_mov_b32_e32 v105, v0
	v_mov_b32_e32 v106, v0
	v_mov_b32_e32 v107, v0
	v_mov_b32_e32 v108, v0
	v_mov_b32_e32 v109, v0
	v_mov_b32_e32 v110, v0
	v_mov_b32_e32 v111, v0
	v_mov_b32_e32 v76, v0
	v_mov_b32_e32 v77, v0
	v_mov_b32_e32 v78, v0
	v_mov_b32_e32 v79, v0
	v_mov_b32_e32 v84, v0
	v_mov_b32_e32 v85, v0
	v_mov_b32_e32 v86, v0
	v_mov_b32_e32 v87, v0
	v_mov_b32_e32 v88, v0
	v_mov_b32_e32 v89, v0
	v_mov_b32_e32 v90, v0
	v_mov_b32_e32 v91, v0
	v_mov_b32_e32 v96, v0
	v_mov_b32_e32 v97, v0
	v_mov_b32_e32 v98, v0
	v_mov_b32_e32 v99, v0
	v_mov_b32_e32 v112, v0
	v_mov_b32_e32 v113, v0
	v_mov_b32_e32 v114, v0
	v_mov_b32_e32 v115, v0
	v_mov_b32_e32 v116, v0
	v_mov_b32_e32 v117, v0
	v_mov_b32_e32 v118, v0
	v_mov_b32_e32 v119, v0
	v_mov_b32_e32 v120, v0
	v_mov_b32_e32 v121, v0
	v_mov_b32_e32 v122, v0
	v_mov_b32_e32 v123, v0
	v_mov_b32_e32 v124, v0
	v_mov_b32_e32 v125, v0
	v_mov_b32_e32 v126, v0
	v_mov_b32_e32 v127, v0
	.p2align	6

; #define EO_LOAD(bt_) do { _Pragma("unroll") for (int mm = 0; mm < 2; ++mm) { const float* xr = xbase + (size_t)(row0 + ((bt_) >> 1) * 128 + (2 * ((bt_) & 1) + mm) * 16) * DM + col0; \
;             _Pragma("unroll") for (int bj = 0; bj < 2; ++bj) _Pragma("unroll") for (int n = 0; n < 2; ++n) xv[(bt_) & 1][mm][bj][n] = *(const f32x4*)(xr + 128 * bj + 4 * n); } } while (0)
; #define EO_FENCE() asm volatile("" ::: "memory")
;     __device__ __forceinline__ void operator()(const f32x4 (&acc)[2][2][4][2], const pg8::Unit& u, int wr, int wc, int fr, int fq) const {
;         const int row0 = u.pm * 256 + wr * 64 + fr, col0 = u.pn * 256 + wc * 32 + 8 * fq;
;         const int s = (u.pm * 256 < NP) ? ((u.pm * 256) >> 12) : 16;
;         const float* gate = mod + s * 3072 + 2048;
;         f32x4 gv[2][2];
; #pragma unroll
;         for (int bj = 0; bj < 2; ++bj)
; #pragma unroll
;             for (int n = 0; n < 2; ++n) gv[bj][n] = *(const f32x4*)(gate + col0 + 128 * bj + 4 * n);
;         const float* xbase = (u.pm * 256 < NP) ? xp : xs - (size_t)NP * DM;
;         f32x4 xv[2][2][2][2];
;     ...
;         EO_LOAD(0); EO_FENCE(); EO_LOAD(1); EO_FENCE();
.LBB0_460:
	s_add_u32 s68, s61, 0x40080
	s_addc_u32 s69, s25, 0
	v_lshl_add_u64 v[164:165], s[68:69], 0, v[152:153]
	s_add_i32 m0, s31, 0xc000
	v_lshl_add_u64 v[216:217], s[68:69], 0, v[154:155]
	global_load_lds_dwordx4 v[164:165], off
	s_add_i32 m0, s31, 0xe000
	s_nop 0
	global_load_lds_dwordx4 v[216:217], off
	s_lshr_b32 s21, s30, 4
	s_cmpk_lt_i32 s30, 0x100
	s_mulk_i32 s21, 0xc00
	s_cselect_b32 s34, s21, 0xc000
	s_cselect_b32 s38, s36, s54
	s_cselect_b32 s39, s37, s55
	s_ashr_i32 s35, s34, 31
	v_lshl_or_b32 v128, s60, 8, v168
	s_lshl_b64 s[34:35], s[34:35], 2
	s_add_u32 s34, s22, s34
	v_ashrrev_i32_e32 v129, 31, v128
	v_lshl_add_u32 v220, s30, 8, v166
	v_and_b32_e32 v220, -2, v220
	s_addc_u32 s35, s23, s35
	v_lshlrev_b64 v[160:161], 2, v[128:129]
	v_or_b32_e32 v188, 16, v220
	v_lshl_add_u64 v[128:129], s[34:35], 0, v[160:161]
	v_ashrrev_i32_e32 v221, 31, v220
	v_ashrrev_i32_e32 v189, 31, v188
	v_or_b32_e32 v204, 32, v220
	v_lshl_add_u64 v[132:133], v[128:129], 0, s[10:11]
	v_add_co_u32_e32 v128, vcc, s52, v128
	v_and_b32_e32 v162, 1, v166
	v_lshlrev_b32_e32 v162, 4, v162
	v_add_u32_e32 v162, 0x800, v162
	v_add_u32_e32 v160, v160, v162
	v_lshl_add_u64 v[162:163], s[38:39], 0, v[160:161]
	v_lshlrev_b64 v[164:165], 12, v[220:221]
	v_lshlrev_b64 v[236:237], 12, v[188:189]
	v_ashrrev_i32_e32 v205, 31, v204
	v_addc_co_u32_e32 v129, vcc, 0, v129, vcc
	v_lshl_add_u64 v[184:185], v[162:163], 0, v[164:165]
	v_lshl_add_u64 v[200:201], v[162:163], 0, v[236:237]
	v_lshlrev_b64 v[238:239], 12, v[204:205]
	global_load_dwordx4 v[136:139], v[128:129], off
	s_nop 0
	global_load_dwordx4 v[128:131], v[132:133], off offset:528
	global_load_dwordx4 v[172:175], v[184:185], off offset:2048
	global_load_dwordx4 v[176:179], v[184:185], off offset:-2048
	global_load_dwordx4 v[140:143], v[132:133], off offset:16
	s_nop 0
	global_load_dwordx4 v[132:135], v[132:133], off offset:512
	s_nop 0
	global_load_dwordx4 v[180:183], v[184:185], off offset:2560
	s_nop 0
	global_load_dwordx4 v[184:187], v[184:185], off offset:-1536
	s_nop 0
	global_load_dwordx4 v[188:191], v[200:201], off offset:-2048
	global_load_dwordx4 v[192:195], v[200:201], off offset:2048
	global_load_dwordx4 v[196:199], v[200:201], off offset:-1536
	s_nop 0
	global_load_dwordx4 v[200:203], v[200:201], off offset:2560
	v_lshl_add_u64 v[216:217], v[162:163], 0, v[238:239]
	v_or_b32_e32 v220, 48, v220
	global_load_dwordx4 v[204:207], v[216:217], off offset:-2048
	global_load_dwordx4 v[208:211], v[216:217], off offset:2048
	global_load_dwordx4 v[212:215], v[216:217], off offset:-1536
	s_nop 0
	global_load_dwordx4 v[216:219], v[216:217], off offset:2560
	v_ashrrev_i32_e32 v221, 31, v220
	v_lshlrev_b64 v[240:241], 12, v[220:221]
	v_lshl_add_u64 v[232:233], v[162:163], 0, v[240:241]
	global_load_dwordx4 v[220:223], v[232:233], off offset:-2048
	global_load_dwordx4 v[224:227], v[232:233], off offset:2048
	global_load_dwordx4 v[228:231], v[232:233], off offset:-1536
	s_nop 0
	global_load_dwordx4 v[232:235], v[232:233], off offset:2560
	v_lshl_add_u64 v[242:243], s[66:67], 0, v[164:165]
	v_lshl_add_u64 v[242:243], v[242:243], 0, v[160:161]
	v_lshl_add_u64 v[236:237], s[66:67], 0, v[236:237]
	v_lshl_add_u64 v[244:245], v[164:165], 0, s[12:13]
	v_lshl_add_u64 v[236:237], v[236:237], 0, v[160:161]
	v_lshl_add_u64 v[246:247], v[162:163], 0, v[244:245]
	s_andn2_b64 s[74:75], exec, s[0:1]
	s_mov_b64 s[0:1], -1
	s_mov_b32 vcc_lo, 0x55555555
	s_mov_b32 vcc_hi, 0x55555555
	v_mov_b32_dpp v248, v124 quad_perm:[1,0,3,2] row_mask:0xf bank_mask:0xf
	v_cndmask_b32_dpp v124, v120, v124, vcc quad_perm:[1,0,3,2] row_mask:0xf bank_mask:0xf
	v_cndmask_b32_e32 v120, v120, v248, vcc
	v_mov_b32_dpp v249, v125 quad_perm:[1,0,3,2] row_mask:0xf bank_mask:0xf
	v_cndmask_b32_dpp v125, v121, v125, vcc quad_perm:[1,0,3,2] row_mask:0xf bank_mask:0xf
	v_cndmask_b32_e32 v121, v121, v249, vcc
	v_mov_b32_dpp v248, v126 quad_perm:[1,0,3,2] row_mask:0xf bank_mask:0xf
	v_cndmask_b32_dpp v126, v122, v126, vcc quad_perm:[1,0,3,2] row_mask:0xf bank_mask:0xf
	v_cndmask_b32_e32 v122, v122, v248, vcc
	v_mov_b32_dpp v249, v127 quad_perm:[1,0,3,2] row_mask:0xf bank_mask:0xf
	v_cndmask_b32_dpp v127, v123, v127, vcc quad_perm:[1,0,3,2] row_mask:0xf bank_mask:0xf
	v_cndmask_b32_e32 v123, v123, v249, vcc
	v_mov_b32_dpp v248, v108 quad_perm:[1,0,3,2] row_mask:0xf bank_mask:0xf
	v_cndmask_b32_dpp v108, v104, v108, vcc quad_perm:[1,0,3,2] row_mask:0xf bank_mask:0xf
	v_cndmask_b32_e32 v104, v104, v248, vcc
	v_mov_b32_dpp v249, v109 quad_perm:[1,0,3,2] row_mask:0xf bank_mask:0xf
	v_cndmask_b32_dpp v109, v105, v109, vcc quad_perm:[1,0,3,2] row_mask:0xf bank_mask:0xf
	v_cndmask_b32_e32 v105, v105, v249, vcc
	v_mov_b32_dpp v248, v110 quad_perm:[1,0,3,2] row_mask:0xf bank_mask:0xf
	v_cndmask_b32_dpp v110, v106, v110, vcc quad_perm:[1,0,3,2] row_mask:0xf bank_mask:0xf
	v_cndmask_b32_e32 v106, v106, v248, vcc
	v_mov_b32_dpp v249, v111 quad_perm:[1,0,3,2] row_mask:0xf bank_mask:0xf
	v_cndmask_b32_dpp v111, v107, v111, vcc quad_perm:[1,0,3,2] row_mask:0xf bank_mask:0xf
	v_cndmask_b32_e32 v107, v107, v249, vcc
	v_mov_b32_dpp v248, v116 quad_perm:[1,0,3,2] row_mask:0xf bank_mask:0xf
	v_cndmask_b32_dpp v116, v112, v116, vcc quad_perm:[1,0,3,2] row_mask:0xf bank_mask:0xf
	v_cndmask_b32_e32 v112, v112, v248, vcc
	v_mov_b32_dpp v249, v117 quad_perm:[1,0,3,2] row_mask:0xf bank_mask:0xf
	v_cndmask_b32_dpp v117, v113, v117, vcc quad_perm:[1,0,3,2] row_mask:0xf bank_mask:0xf
	v_cndmask_b32_e32 v113, v113, v249, vcc
	v_mov_b32_dpp v248, v118 quad_perm:[1,0,3,2] row_mask:0xf bank_mask:0xf
	v_cndmask_b32_dpp v118, v114, v118, vcc quad_perm:[1,0,3,2] row_mask:0xf bank_mask:0xf
	v_cndmask_b32_e32 v114, v114, v248, vcc
	v_mov_b32_dpp v249, v119 quad_perm:[1,0,3,2] row_mask:0xf bank_mask:0xf
	v_cndmask_b32_dpp v119, v115, v119, vcc quad_perm:[1,0,3,2] row_mask:0xf bank_mask:0xf
	v_cndmask_b32_e32 v115, v115, v249, vcc
	v_mov_b32_dpp v248, v100 quad_perm:[1,0,3,2] row_mask:0xf bank_mask:0xf
	v_cndmask_b32_dpp v100, v92, v100, vcc quad_perm:[1,0,3,2] row_mask:0xf bank_mask:0xf
	v_cndmask_b32_e32 v92, v92, v248, vcc
	v_mov_b32_dpp v249, v101 quad_perm:[1,0,3,2] row_mask:0xf bank_mask:0xf
	v_cndmask_b32_dpp v101, v93, v101, vcc quad_perm:[1,0,3,2] row_mask:0xf bank_mask:0xf
	v_cndmask_b32_e32 v93, v93, v249, vcc
	v_mov_b32_dpp v248, v102 quad_perm:[1,0,3,2] row_mask:0xf bank_mask:0xf
	v_cndmask_b32_dpp v102, v94, v102, vcc quad_perm:[1,0,3,2] row_mask:0xf bank_mask:0xf
	v_cndmask_b32_e32 v94, v94, v248, vcc
	v_mov_b32_dpp v249, v103 quad_perm:[1,0,3,2] row_mask:0xf bank_mask:0xf
	v_cndmask_b32_dpp v103, v95, v103, vcc quad_perm:[1,0,3,2] row_mask:0xf bank_mask:0xf
	v_cndmask_b32_e32 v95, v95, v249, vcc
	v_mov_b32_dpp v248, v96 quad_perm:[1,0,3,2] row_mask:0xf bank_mask:0xf
	v_cndmask_b32_dpp v96, v88, v96, vcc quad_perm:[1,0,3,2] row_mask:0xf bank_mask:0xf
	v_cndmask_b32_e32 v88, v88, v248, vcc
	v_mov_b32_dpp v249, v97 quad_perm:[1,0,3,2] row_mask:0xf bank_mask:0xf
	v_cndmask_b32_dpp v97, v89, v97, vcc quad_perm:[1,0,3,2] row_mask:0xf bank_mask:0xf
	v_cndmask_b32_e32 v89, v89, v249, vcc
	v_mov_b32_dpp v248, v98 quad_perm:[1,0,3,2] row_mask:0xf bank_mask:0xf
	v_cndmask_b32_dpp v98, v90, v98, vcc quad_perm:[1,0,3,2] row_mask:0xf bank_mask:0xf
	v_cndmask_b32_e32 v90, v90, v248, vcc
	v_mov_b32_dpp v249, v99 quad_perm:[1,0,3,2] row_mask:0xf bank_mask:0xf
	v_cndmask_b32_dpp v99, v91, v99, vcc quad_perm:[1,0,3,2] row_mask:0xf bank_mask:0xf
	v_cndmask_b32_e32 v91, v91, v249, vcc
	v_mov_b32_dpp v248, v80 quad_perm:[1,0,3,2] row_mask:0xf bank_mask:0xf
	v_cndmask_b32_dpp v80, v72, v80, vcc quad_perm:[1,0,3,2] row_mask:0xf bank_mask:0xf
	v_cndmask_b32_e32 v72, v72, v248, vcc
	v_mov_b32_dpp v249, v81 quad_perm:[1,0,3,2] row_mask:0xf bank_mask:0xf
	v_cndmask_b32_dpp v81, v73, v81, vcc quad_perm:[1,0,3,2] row_mask:0xf bank_mask:0xf
	v_cndmask_b32_e32 v73, v73, v249, vcc
	v_mov_b32_dpp v248, v82 quad_perm:[1,0,3,2] row_mask:0xf bank_mask:0xf
	v_cndmask_b32_dpp v82, v74, v82, vcc quad_perm:[1,0,3,2] row_mask:0xf bank_mask:0xf
	v_cndmask_b32_e32 v74, v74, v248, vcc
	v_mov_b32_dpp v249, v83 quad_perm:[1,0,3,2] row_mask:0xf bank_mask:0xf
	v_cndmask_b32_dpp v83, v75, v83, vcc quad_perm:[1,0,3,2] row_mask:0xf bank_mask:0xf
	v_cndmask_b32_e32 v75, v75, v249, vcc
	v_mov_b32_dpp v248, v84 quad_perm:[1,0,3,2] row_mask:0xf bank_mask:0xf
	v_cndmask_b32_dpp v84, v76, v84, vcc quad_perm:[1,0,3,2] row_mask:0xf bank_mask:0xf
	v_cndmask_b32_e32 v76, v76, v248, vcc
	v_mov_b32_dpp v249, v85 quad_perm:[1,0,3,2] row_mask:0xf bank_mask:0xf
	v_cndmask_b32_dpp v85, v77, v85, vcc quad_perm:[1,0,3,2] row_mask:0xf bank_mask:0xf
	v_cndmask_b32_e32 v77, v77, v249, vcc
	v_mov_b32_dpp v248, v86 quad_perm:[1,0,3,2] row_mask:0xf bank_mask:0xf
	v_cndmask_b32_dpp v86, v78, v86, vcc quad_perm:[1,0,3,2] row_mask:0xf bank_mask:0xf
	v_cndmask_b32_e32 v78, v78, v248, vcc
	v_mov_b32_dpp v249, v87 quad_perm:[1,0,3,2] row_mask:0xf bank_mask:0xf
	v_cndmask_b32_dpp v87, v79, v87, vcc quad_perm:[1,0,3,2] row_mask:0xf bank_mask:0xf
	v_cndmask_b32_e32 v79, v79, v249, vcc
	v_mov_b32_dpp v248, v68 quad_perm:[1,0,3,2] row_mask:0xf bank_mask:0xf
	v_cndmask_b32_dpp v68, v64, v68, vcc quad_perm:[1,0,3,2] row_mask:0xf bank_mask:0xf
	v_cndmask_b32_e32 v64, v64, v248, vcc
	v_mov_b32_dpp v249, v69 quad_perm:[1,0,3,2] row_mask:0xf bank_mask:0xf
	v_cndmask_b32_dpp v69, v65, v69, vcc quad_perm:[1,0,3,2] row_mask:0xf bank_mask:0xf
	v_cndmask_b32_e32 v65, v65, v249, vcc
	v_mov_b32_dpp v248, v70 quad_perm:[1,0,3,2] row_mask:0xf bank_mask:0xf
	v_cndmask_b32_dpp v70, v66, v70, vcc quad_perm:[1,0,3,2] row_mask:0xf bank_mask:0xf
	v_cndmask_b32_e32 v66, v66, v248, vcc
	v_mov_b32_dpp v249, v71 quad_perm:[1,0,3,2] row_mask:0xf bank_mask:0xf
	v_cndmask_b32_dpp v71, v67, v71, vcc quad_perm:[1,0,3,2] row_mask:0xf bank_mask:0xf
	v_cndmask_b32_e32 v67, v67, v249, vcc
	v_mov_b32_dpp v248, v60 quad_perm:[1,0,3,2] row_mask:0xf bank_mask:0xf
	v_cndmask_b32_dpp v60, v56, v60, vcc quad_perm:[1,0,3,2] row_mask:0xf bank_mask:0xf
	v_cndmask_b32_e32 v56, v56, v248, vcc
	v_mov_b32_dpp v249, v61 quad_perm:[1,0,3,2] row_mask:0xf bank_mask:0xf
	v_cndmask_b32_dpp v61, v57, v61, vcc quad_perm:[1,0,3,2] row_mask:0xf bank_mask:0xf
	v_cndmask_b32_e32 v57, v57, v249, vcc
	v_mov_b32_dpp v248, v62 quad_perm:[1,0,3,2] row_mask:0xf bank_mask:0xf
	v_cndmask_b32_dpp v62, v58, v62, vcc quad_perm:[1,0,3,2] row_mask:0xf bank_mask:0xf
	v_cndmask_b32_e32 v58, v58, v248, vcc
	v_mov_b32_dpp v249, v63 quad_perm:[1,0,3,2] row_mask:0xf bank_mask:0xf
	v_cndmask_b32_dpp v63, v59, v63, vcc quad_perm:[1,0,3,2] row_mask:0xf bank_mask:0xf
	v_cndmask_b32_e32 v59, v59, v249, vcc
	v_mov_b32_dpp v248, v44 quad_perm:[1,0,3,2] row_mask:0xf bank_mask:0xf
	v_cndmask_b32_dpp v44, v40, v44, vcc quad_perm:[1,0,3,2] row_mask:0xf bank_mask:0xf
	v_cndmask_b32_e32 v40, v40, v248, vcc
	v_mov_b32_dpp v249, v45 quad_perm:[1,0,3,2] row_mask:0xf bank_mask:0xf
	v_cndmask_b32_dpp v45, v41, v45, vcc quad_perm:[1,0,3,2] row_mask:0xf bank_mask:0xf
	v_cndmask_b32_e32 v41, v41, v249, vcc
	v_mov_b32_dpp v248, v46 quad_perm:[1,0,3,2] row_mask:0xf bank_mask:0xf
	v_cndmask_b32_dpp v46, v42, v46, vcc quad_perm:[1,0,3,2] row_mask:0xf bank_mask:0xf
	v_cndmask_b32_e32 v42, v42, v248, vcc
	v_mov_b32_dpp v249, v47 quad_perm:[1,0,3,2] row_mask:0xf bank_mask:0xf
	v_cndmask_b32_dpp v47, v43, v47, vcc quad_perm:[1,0,3,2] row_mask:0xf bank_mask:0xf
	v_cndmask_b32_e32 v43, v43, v249, vcc
	v_mov_b32_dpp v248, v52 quad_perm:[1,0,3,2] row_mask:0xf bank_mask:0xf
	v_cndmask_b32_dpp v52, v48, v52, vcc quad_perm:[1,0,3,2] row_mask:0xf bank_mask:0xf
	v_cndmask_b32_e32 v48, v48, v248, vcc
	v_mov_b32_dpp v249, v53 quad_perm:[1,0,3,2] row_mask:0xf bank_mask:0xf
	v_cndmask_b32_dpp v53, v49, v53, vcc quad_perm:[1,0,3,2] row_mask:0xf bank_mask:0xf
	v_cndmask_b32_e32 v49, v49, v249, vcc
	v_mov_b32_dpp v248, v54 quad_perm:[1,0,3,2] row_mask:0xf bank_mask:0xf
	v_cndmask_b32_dpp v54, v50, v54, vcc quad_perm:[1,0,3,2] row_mask:0xf bank_mask:0xf
	v_cndmask_b32_e32 v50, v50, v248, vcc
	v_mov_b32_dpp v249, v55 quad_perm:[1,0,3,2] row_mask:0xf bank_mask:0xf
	v_cndmask_b32_dpp v55, v51, v55, vcc quad_perm:[1,0,3,2] row_mask:0xf bank_mask:0xf
	v_cndmask_b32_e32 v51, v51, v249, vcc
	v_mov_b32_dpp v248, v32 quad_perm:[1,0,3,2] row_mask:0xf bank_mask:0xf
	v_cndmask_b32_dpp v32, v28, v32, vcc quad_perm:[1,0,3,2] row_mask:0xf bank_mask:0xf
	v_cndmask_b32_e32 v28, v28, v248, vcc
	v_mov_b32_dpp v249, v33 quad_perm:[1,0,3,2] row_mask:0xf bank_mask:0xf
	v_cndmask_b32_dpp v33, v29, v33, vcc quad_perm:[1,0,3,2] row_mask:0xf bank_mask:0xf
	v_cndmask_b32_e32 v29, v29, v249, vcc
	v_mov_b32_dpp v248, v34 quad_perm:[1,0,3,2] row_mask:0xf bank_mask:0xf
	v_cndmask_b32_dpp v34, v30, v34, vcc quad_perm:[1,0,3,2] row_mask:0xf bank_mask:0xf
	v_cndmask_b32_e32 v30, v30, v248, vcc
	v_mov_b32_dpp v249, v35 quad_perm:[1,0,3,2] row_mask:0xf bank_mask:0xf
	v_cndmask_b32_dpp v35, v31, v35, vcc quad_perm:[1,0,3,2] row_mask:0xf bank_mask:0xf
	v_cndmask_b32_e32 v31, v31, v249, vcc
	v_mov_b32_dpp v248, v36 quad_perm:[1,0,3,2] row_mask:0xf bank_mask:0xf
	v_cndmask_b32_dpp v36, v24, v36, vcc quad_perm:[1,0,3,2] row_mask:0xf bank_mask:0xf
	v_cndmask_b32_e32 v24, v24, v248, vcc
	v_mov_b32_dpp v249, v37 quad_perm:[1,0,3,2] row_mask:0xf bank_mask:0xf
	v_cndmask_b32_dpp v37, v25, v37, vcc quad_perm:[1,0,3,2] row_mask:0xf bank_mask:0xf
	v_cndmask_b32_e32 v25, v25, v249, vcc
	v_mov_b32_dpp v248, v38 quad_perm:[1,0,3,2] row_mask:0xf bank_mask:0xf
	v_cndmask_b32_dpp v38, v26, v38, vcc quad_perm:[1,0,3,2] row_mask:0xf bank_mask:0xf
	v_cndmask_b32_e32 v26, v26, v248, vcc
	v_mov_b32_dpp v249, v39 quad_perm:[1,0,3,2] row_mask:0xf bank_mask:0xf
	v_cndmask_b32_dpp v39, v27, v39, vcc quad_perm:[1,0,3,2] row_mask:0xf bank_mask:0xf
	v_cndmask_b32_e32 v27, v27, v249, vcc
	v_mov_b32_dpp v248, v16 quad_perm:[1,0,3,2] row_mask:0xf bank_mask:0xf
	v_cndmask_b32_dpp v16, v8, v16, vcc quad_perm:[1,0,3,2] row_mask:0xf bank_mask:0xf
	v_cndmask_b32_e32 v8, v8, v248, vcc
	v_mov_b32_dpp v249, v17 quad_perm:[1,0,3,2] row_mask:0xf bank_mask:0xf
	v_cndmask_b32_dpp v17, v9, v17, vcc quad_perm:[1,0,3,2] row_mask:0xf bank_mask:0xf
	v_cndmask_b32_e32 v9, v9, v249, vcc
	v_mov_b32_dpp v248, v18 quad_perm:[1,0,3,2] row_mask:0xf bank_mask:0xf
	v_cndmask_b32_dpp v18, v10, v18, vcc quad_perm:[1,0,3,2] row_mask:0xf bank_mask:0xf
	v_cndmask_b32_e32 v10, v10, v248, vcc
	v_mov_b32_dpp v249, v19 quad_perm:[1,0,3,2] row_mask:0xf bank_mask:0xf
	v_cndmask_b32_dpp v19, v11, v19, vcc quad_perm:[1,0,3,2] row_mask:0xf bank_mask:0xf
	v_cndmask_b32_e32 v11, v11, v249, vcc
	v_mov_b32_dpp v248, v20 quad_perm:[1,0,3,2] row_mask:0xf bank_mask:0xf
	v_cndmask_b32_dpp v20, v12, v20, vcc quad_perm:[1,0,3,2] row_mask:0xf bank_mask:0xf
	v_cndmask_b32_e32 v12, v12, v248, vcc
	v_mov_b32_dpp v249, v21 quad_perm:[1,0,3,2] row_mask:0xf bank_mask:0xf
	v_cndmask_b32_dpp v21, v13, v21, vcc quad_perm:[1,0,3,2] row_mask:0xf bank_mask:0xf
	v_cndmask_b32_e32 v13, v13, v249, vcc
	v_mov_b32_dpp v248, v22 quad_perm:[1,0,3,2] row_mask:0xf bank_mask:0xf
	v_cndmask_b32_dpp v22, v14, v22, vcc quad_perm:[1,0,3,2] row_mask:0xf bank_mask:0xf
	v_cndmask_b32_e32 v14, v14, v248, vcc
	v_mov_b32_dpp v249, v23 quad_perm:[1,0,3,2] row_mask:0xf bank_mask:0xf
	v_cndmask_b32_dpp v23, v15, v23, vcc quad_perm:[1,0,3,2] row_mask:0xf bank_mask:0xf
	v_cndmask_b32_e32 v15, v15, v249, vcc
	v_mov_b32_dpp v248, v4 quad_perm:[1,0,3,2] row_mask:0xf bank_mask:0xf
	v_cndmask_b32_dpp v4, v0, v4, vcc quad_perm:[1,0,3,2] row_mask:0xf bank_mask:0xf
	v_cndmask_b32_e32 v0, v0, v248, vcc
	v_mov_b32_dpp v249, v5 quad_perm:[1,0,3,2] row_mask:0xf bank_mask:0xf
	v_cndmask_b32_dpp v5, v1, v5, vcc quad_perm:[1,0,3,2] row_mask:0xf bank_mask:0xf
	v_cndmask_b32_e32 v1, v1, v249, vcc
	v_mov_b32_dpp v248, v6 quad_perm:[1,0,3,2] row_mask:0xf bank_mask:0xf
	v_cndmask_b32_dpp v6, v2, v6, vcc quad_perm:[1,0,3,2] row_mask:0xf bank_mask:0xf
	v_cndmask_b32_e32 v2, v2, v248, vcc
	v_mov_b32_dpp v249, v7 quad_perm:[1,0,3,2] row_mask:0xf bank_mask:0xf
	v_cndmask_b32_dpp v7, v3, v7, vcc quad_perm:[1,0,3,2] row_mask:0xf bank_mask:0xf
	v_cndmask_b32_e32 v3, v3, v249, vcc
	s_waitcnt vmcnt(0)
; #define EO_LOAD(bt_) do { _Pragma("unroll") for (int mm = 0; mm < 2; ++mm) { const float* xr = xbase + (size_t)(row0 + ((bt_) >> 1) * 128 + (2 * ((bt_) & 1) + mm) * 16) * DM + col0; \
;             _Pragma("unroll") for (int bj = 0; bj < 2; ++bj) _Pragma("unroll") for (int n = 0; n < 2; ++n) xv[(bt_) & 1][mm][bj][n] = *(const f32x4*)(xr + 128 * bj + 4 * n); } } while (0)
; #define EO_FENCE() asm volatile("" ::: "memory")
;     __device__ __forceinline__ void operator()(const f32x4 (&acc)[2][2][4][2], const pg8::Unit& u, int wr, int wc, int fr, int fq) const {
;     ...
;         EO_LOAD(0); EO_FENCE(); EO_LOAD(1); EO_FENCE();
;         EO_STORE(0); EO_FENCE(); EO_LOAD(2); EO_FENCE();
;         EO_STORE(1); EO_FENCE(); EO_LOAD(3); EO_FENCE();
;         EO_STORE(2); EO_FENCE(); EO_STORE(3);
	v_cndmask_b32_e32 v136, v140, v136, vcc
	v_cndmask_b32_e32 v132, v128, v132, vcc
	v_cndmask_b32_e32 v137, v141, v137, vcc
	v_cndmask_b32_e32 v133, v129, v133, vcc
	v_cndmask_b32_e32 v138, v142, v138, vcc
	v_cndmask_b32_e32 v134, v130, v134, vcc
	v_cndmask_b32_e32 v139, v143, v139, vcc
	v_cndmask_b32_e32 v135, v131, v135, vcc
	v_mov_b32_e32 v140, v136
	v_mov_b32_e32 v128, v132
	v_mov_b32_e32 v141, v137
	v_mov_b32_e32 v129, v133
	v_mov_b32_e32 v142, v138
	v_mov_b32_e32 v130, v134
	v_mov_b32_e32 v143, v139
	v_mov_b32_e32 v131, v135
	v_pk_fma_f32 v[122:123], v[122:123], v[142:143], v[174:175]
	v_pk_fma_f32 v[126:127], v[126:127], v[138:139], v[178:179]
	v_pk_fma_f32 v[124:125], v[124:125], v[136:137], v[176:177]
	v_pk_fma_f32 v[120:121], v[120:121], v[140:141], v[172:173]
	v_pk_fma_f32 v[110:111], v[110:111], v[134:135], v[186:187]
	v_pk_fma_f32 v[108:109], v[108:109], v[132:133], v[184:185]
	v_pk_fma_f32 v[106:107], v[106:107], v[130:131], v[182:183]
	v_pk_fma_f32 v[104:105], v[104:105], v[128:129], v[180:181]
	v_pk_fma_f32 v[118:119], v[118:119], v[138:139], v[190:191]
	v_pk_fma_f32 v[116:117], v[116:117], v[136:137], v[188:189]
	v_pk_fma_f32 v[114:115], v[114:115], v[142:143], v[194:195]
	v_pk_fma_f32 v[112:113], v[112:113], v[140:141], v[192:193]
	v_pk_fma_f32 v[102:103], v[102:103], v[134:135], v[198:199]
	v_pk_fma_f32 v[100:101], v[100:101], v[132:133], v[196:197]
	v_pk_fma_f32 v[94:95], v[94:95], v[130:131], v[202:203]
	v_pk_fma_f32 v[92:93], v[92:93], v[128:129], v[200:201]
	global_store_dwordx4 v[242:243], v[124:127], off offset:-2048
	global_store_dwordx4 v[242:243], v[120:123], off offset:2048
	global_store_dwordx4 v[242:243], v[108:111], off offset:-1536
	global_store_dwordx4 v[242:243], v[104:107], off offset:2560
	global_store_dwordx4 v[236:237], v[116:119], off offset:-2048
	global_store_dwordx4 v[236:237], v[112:115], off offset:2048
	global_store_dwordx4 v[236:237], v[100:103], off offset:-1536
	global_store_dwordx4 v[236:237], v[92:95], off offset:2560
	v_lshl_add_u64 v[172:173], v[164:165], 0, s[14:15]
	v_lshl_add_u64 v[174:175], s[66:67], 0, v[238:239]
	v_lshl_add_u64 v[124:125], v[162:163], 0, v[172:173]
	v_lshl_add_u64 v[174:175], v[174:175], 0, v[160:161]
	v_pk_fma_f32 v[74:75], v[74:75], v[130:131], v[218:219]
	v_pk_fma_f32 v[72:73], v[72:73], v[128:129], v[216:217]
	global_load_dwordx4 v[92:95], v[246:247], off offset:2048
	global_load_dwordx4 v[100:103], v[246:247], off offset:-2048
	global_load_dwordx4 v[104:107], v[246:247], off offset:2560
	global_load_dwordx4 v[108:111], v[246:247], off offset:-1536
	global_load_dwordx4 v[112:115], v[124:125], off offset:2048
	global_load_dwordx4 v[116:119], v[124:125], off offset:-2048
	global_load_dwordx4 v[120:123], v[124:125], off offset:2560
	s_nop 0
	global_load_dwordx4 v[124:127], v[124:125], off offset:-1536
	v_pk_fma_f32 v[82:83], v[82:83], v[134:135], v[214:215]
	v_pk_fma_f32 v[80:81], v[80:81], v[132:133], v[212:213]
	global_store_dwordx4 v[174:175], v[72:75], off offset:2560
	global_store_dwordx4 v[174:175], v[80:83], off offset:-1536
	v_pk_fma_f32 v[98:99], v[98:99], v[138:139], v[206:207]
	v_lshl_add_u64 v[72:73], s[66:67], 0, v[240:241]
	v_lshl_add_u64 v[80:81], v[72:73], 0, v[160:161]
	v_pk_fma_f32 v[74:75], v[86:87], v[138:139], v[222:223]
	v_pk_fma_f32 v[72:73], v[84:85], v[136:137], v[220:221]
	v_pk_fma_f32 v[96:97], v[96:97], v[136:137], v[204:205]
	v_pk_fma_f32 v[90:91], v[90:91], v[142:143], v[210:211]
	v_pk_fma_f32 v[88:89], v[88:89], v[140:141], v[208:209]
	global_store_dwordx4 v[80:81], v[72:75], off offset:-2048
	v_pk_fma_f32 v[70:71], v[70:71], v[134:135], v[230:231]
	v_pk_fma_f32 v[68:69], v[68:69], v[132:133], v[228:229]
	v_pk_fma_f32 v[74:75], v[78:79], v[142:143], v[226:227]
	v_pk_fma_f32 v[72:73], v[76:77], v[140:141], v[224:225]
	v_pk_fma_f32 v[66:67], v[66:67], v[130:131], v[234:235]
	v_pk_fma_f32 v[64:65], v[64:65], v[128:129], v[232:233]
	global_store_dwordx4 v[174:175], v[96:99], off offset:-2048
	global_store_dwordx4 v[174:175], v[88:91], off offset:2048
	global_store_dwordx4 v[80:81], v[72:75], off offset:2048
	global_store_dwordx4 v[80:81], v[68:71], off offset:-1536
	global_store_dwordx4 v[80:81], v[64:67], off offset:2560
	v_lshl_add_u64 v[174:175], v[164:165], 0, s[16:17]
	v_lshl_add_u64 v[76:77], v[162:163], 0, v[174:175]
	global_load_dwordx4 v[64:67], v[76:77], off offset:-2048
	global_load_dwordx4 v[68:71], v[76:77], off offset:2048
	global_load_dwordx4 v[72:75], v[76:77], off offset:-1536
	s_nop 0
	global_load_dwordx4 v[76:79], v[76:77], off offset:2560
	v_lshl_add_u64 v[164:165], v[164:165], 0, s[18:19]
	v_lshl_add_u64 v[96:97], v[162:163], 0, v[164:165]
	global_load_dwordx4 v[80:83], v[96:97], off offset:-2048
	global_load_dwordx4 v[84:87], v[96:97], off offset:2048
	global_load_dwordx4 v[88:91], v[96:97], off offset:-1536
	s_nop 0
	global_load_dwordx4 v[96:99], v[96:97], off offset:2560
	v_lshl_add_u64 v[162:163], s[66:67], 0, v[244:245]
	v_lshl_add_u64 v[172:173], s[66:67], 0, v[172:173]
	v_lshl_add_u64 v[174:175], s[66:67], 0, v[174:175]
	v_lshl_add_u64 v[162:163], v[162:163], 0, v[160:161]
	v_lshl_add_u64 v[172:173], v[172:173], 0, v[160:161]
	v_lshl_add_u64 v[174:175], v[174:175], 0, v[160:161]
	s_waitcnt vmcnt(23)
; #define EO_LOAD(bt_) do { _Pragma("unroll") for (int mm = 0; mm < 2; ++mm) { const float* xr = xbase + (size_t)(row0 + ((bt_) >> 1) * 128 + (2 * ((bt_) & 1) + mm) * 16) * DM + col0; \
;             _Pragma("unroll") for (int bj = 0; bj < 2; ++bj) _Pragma("unroll") for (int n = 0; n < 2; ++n) xv[(bt_) & 1][mm][bj][n] = *(const f32x4*)(xr + 128 * bj + 4 * n); } } while (0)
; #define EO_FENCE() asm volatile("" ::: "memory")
;     __device__ __forceinline__ void operator()(const f32x4 (&acc)[2][2][4][2], const pg8::Unit& u, int wr, int wc, int fr, int fq) const {
;     ...
;         EO_LOAD(0); EO_FENCE(); EO_LOAD(1); EO_FENCE();
;         EO_STORE(0); EO_FENCE(); EO_LOAD(2); EO_FENCE();
;         EO_STORE(1); EO_FENCE(); EO_LOAD(3); EO_FENCE();
;         EO_STORE(2); EO_FENCE(); EO_STORE(3);
	v_pk_fma_f32 v[58:59], v[58:59], v[142:143], v[94:95]
	s_waitcnt vmcnt(22)
	v_pk_fma_f32 v[62:63], v[62:63], v[138:139], v[102:103]
	v_pk_fma_f32 v[60:61], v[60:61], v[136:137], v[100:101]
	v_pk_fma_f32 v[56:57], v[56:57], v[140:141], v[92:93]
	s_waitcnt vmcnt(20)
	v_pk_fma_f32 v[46:47], v[46:47], v[134:135], v[110:111]
	v_pk_fma_f32 v[44:45], v[44:45], v[132:133], v[108:109]
	v_pk_fma_f32 v[42:43], v[42:43], v[130:131], v[106:107]
	v_pk_fma_f32 v[40:41], v[40:41], v[128:129], v[104:105]
	s_waitcnt vmcnt(18)
	v_pk_fma_f32 v[54:55], v[54:55], v[138:139], v[118:119]
	v_pk_fma_f32 v[52:53], v[52:53], v[136:137], v[116:117]
	v_pk_fma_f32 v[50:51], v[50:51], v[142:143], v[114:115]
	v_pk_fma_f32 v[48:49], v[48:49], v[140:141], v[112:113]
	s_waitcnt vmcnt(16)
	v_pk_fma_f32 v[34:35], v[34:35], v[134:135], v[126:127]
	v_pk_fma_f32 v[32:33], v[32:33], v[132:133], v[124:125]
	v_pk_fma_f32 v[30:31], v[30:31], v[130:131], v[122:123]
	v_pk_fma_f32 v[28:29], v[28:29], v[128:129], v[120:121]
	global_store_dwordx4 v[162:163], v[60:63], off offset:-2048
	global_store_dwordx4 v[162:163], v[56:59], off offset:2048
	global_store_dwordx4 v[162:163], v[44:47], off offset:-1536
	global_store_dwordx4 v[162:163], v[40:43], off offset:2560
	global_store_dwordx4 v[172:173], v[52:55], off offset:-2048
	global_store_dwordx4 v[172:173], v[48:51], off offset:2048
	global_store_dwordx4 v[172:173], v[32:35], off offset:-1536
	global_store_dwordx4 v[172:173], v[28:31], off offset:2560
	s_waitcnt vmcnt(14)
	v_pk_fma_f32 v[26:27], v[26:27], v[142:143], v[70:71]
	s_waitcnt vmcnt(13)
	v_pk_fma_f32 v[18:19], v[18:19], v[134:135], v[74:75]
	s_waitcnt vmcnt(12)
	v_pk_fma_f32 v[10:11], v[10:11], v[130:131], v[78:79]
	v_pk_fma_f32 v[8:9], v[8:9], v[128:129], v[76:77]
	v_pk_fma_f32 v[16:17], v[16:17], v[132:133], v[72:73]
	global_store_dwordx4 v[174:175], v[8:11], off offset:2560
	global_store_dwordx4 v[174:175], v[16:19], off offset:-1536
	v_pk_fma_f32 v[30:31], v[38:39], v[138:139], v[66:67]
	v_lshl_add_u64 v[8:9], s[66:67], 0, v[164:165]
	v_lshl_add_u64 v[16:17], v[8:9], 0, v[160:161]
	s_waitcnt vmcnt(13)
	v_pk_fma_f32 v[10:11], v[22:23], v[138:139], v[82:83]
	v_pk_fma_f32 v[8:9], v[20:21], v[136:137], v[80:81]
	v_pk_fma_f32 v[28:29], v[36:37], v[136:137], v[64:65]
	v_pk_fma_f32 v[24:25], v[24:25], v[140:141], v[68:69]
	global_store_dwordx4 v[16:17], v[8:11], off offset:-2048
	s_waitcnt vmcnt(12)
	v_pk_fma_f32 v[6:7], v[6:7], v[134:135], v[90:91]
	v_pk_fma_f32 v[4:5], v[4:5], v[132:133], v[88:89]
	v_pk_fma_f32 v[10:11], v[14:15], v[142:143], v[86:87]
	v_pk_fma_f32 v[8:9], v[12:13], v[140:141], v[84:85]
	s_waitcnt vmcnt(11)
	v_pk_fma_f32 v[2:3], v[2:3], v[130:131], v[98:99]
	v_pk_fma_f32 v[0:1], v[0:1], v[128:129], v[96:97]
	global_store_dwordx4 v[174:175], v[28:31], off offset:-2048
	global_store_dwordx4 v[174:175], v[24:27], off offset:2048
	global_store_dwordx4 v[16:17], v[8:11], off offset:2048
	global_store_dwordx4 v[16:17], v[4:7], off offset:-1536
	global_store_dwordx4 v[16:17], v[0:3], off offset:2560
	s_mov_b64 vcc, s[74:75]
	s_cbranch_vccnz .LBB0_453
	s_andn2_b64 vcc, exec, s[4:5]
	s_cbranch_vccnz .LBB0_452
	s_barrier
	s_branch .LBB0_452
	.p2align	6
